# GDN scan: gate/u/g_last loads moved to the top of each half-step with a 2-chunk prefetch distance (landing register sets + copies); only two counted vmcnt waits left in the loop
# baseline (speedup 1.0000x reference)
; #define LAS __attribute__((address_space(3)))
; #define SC_ISSUE(P, n) do { const int nn_ = (n) < 64 ? (n) : 63; const unsigned char* Gn_ = G0 + (size_t)nn_ * (8 * 40960); _Pragma("unroll") for (int mt = 0; mt < 4; ++mt) P[mt] = __builtin_nontemporal_load((const u32x4*)(Gn_ + mt * 8192 + tid * 16)); } while (0)
; #define SC_COMMIT(P, stage) do { LAS unsigned char* nb_ = lds + (stage) * 36864; _Pragma("unroll") for (int mt = 0; mt < 4; ++mt) *(LAS u32x4*)(nb_ + mt * 9216 + prow * 144 + pc * 16) = P[mt]; } while (0)
; #define SC_UNEXT(n) do { const int nn_ = (n) < 64 ? (n) : 63; const bf16* UT_ = (const bf16*)(G0 + (size_t)nn_ * (8 * 40960) + 32768); _Pragma("unroll") for (int mb = 0; mb < 4; ++mb) un[mb] = __builtin_nontemporal_load((const u32x2*)(UT_ + e * 64 + 16 * mb + 4 * q4)); gln = glast[(b * 64 + nn_) * 8 + h]; } while (0)
; DI void gdn_scan(int b, int h, const unsigned char* G, const float* glast, const bf16* PSg, const float* g_gdn, bf16* MIXA, LAS unsigned char* lds, int tid) {
;     const int wave = __builtin_amdgcn_readfirstlane(tid >> 6), lane = tid & 63, m16 = lane & 15, q4 = lane >> 4;
;     const int prow = tid >> 3, pc = tid & 7;
;     const int e = 16 * (wave & 3) + m16;
;     f32x4 S[4];
; #pragma unroll
;     for (int i = 0; i < 4; ++i) S[i] = (f32x4){0.f, 0.f, 0.f, 0.f};
;     u32x4 pA[4], pB[4]; u32x2 un[4]; float gln; u32x4 gt[2];
;     const unsigned char* G0 = G + (size_t)(b * 512 + h) * 40960;
;     const int fr0 = (tid & 255) >> 3, fc8 = tid & 7;
;     float gd[8];
;     { const f32x4 g0 = *(const f32x4*)(g_gdn + 8 * fc8), g1 = *(const f32x4*)(g_gdn + 8 * fc8 + 4); gd[0] = g0[0]; gd[1] = g0[1]; gd[2] = g0[2]; gd[3] = g0[3]; gd[4] = g1[0]; gd[5] = g1[1]; gd[6] = g1[2]; gd[7] = g1[3]; }
;     ...
;     SC_ISSUE(pA, 0); SC_ISSUE(pB, 1);
;     SC_UNEXT(0);
;     SC_COMMIT(pA, 0);
;     __syncthreads();
.LBB0_818:
	s_ashr_i32 s3, s44, 3
	s_and_b32 s46, s44, 7
	s_lshl_b32 s22, s3, 9
	v_readfirstlane_b32 s20, v197
	s_or_b32 s0, s22, s46
	s_and_b32 s2, s43, 7
	s_lshr_b32 s10, s20, 2
	s_ashr_i32 s1, s0, 31
	s_mul_i32 s16, s0, 0xa000
	s_mul_hi_i32 s17, s0, 0xa000
	s_add_u32 s16, s80, s16
	s_addc_u32 s17, s81, s17
	v_lshl_add_u64 v[94:95], s[16:17], 0, v[80:81]
	s_waitcnt vmcnt(0)
	v_add_co_u32_e32 v8, vcc, s31, v94
	global_load_dwordx4 v[4:7], v[78:79], off
	global_load_dwordx4 v[0:3], v[78:79], off offset:16
	v_addc_co_u32_e32 v9, vcc, 0, v95, vcc
	global_load_dwordx4 v[24:27], v[94:95], off
	global_load_dwordx4 v[28:31], v[8:9], off
	v_add_co_u32_e32 v8, vcc, s34, v94
	v_and_or_b32 v44, s10, 48, v93
	s_nop 0
	v_addc_co_u32_e32 v9, vcc, 0, v95, vcc
	v_add_co_u32_e32 v10, vcc, s35, v94
	v_lshlrev_b32_e32 v76, 7, v44
	s_nop 0
	v_addc_co_u32_e32 v11, vcc, 0, v95, vcc
	global_load_dwordx4 v[32:35], v[8:9], off
	global_load_dwordx4 v[36:39], v[10:11], off
	v_add_co_u32_e32 v8, vcc, s36, v94
	v_lshl_add_u64 v[40:41], s[16:17], 0, v[76:77]
	s_nop 0
	v_addc_co_u32_e32 v9, vcc, 0, v95, vcc
	v_add_co_u32_e32 v12, vcc, s37, v94
	s_lshl_b64 s[0:1], s[0:1], 2
	s_nop 0
	v_addc_co_u32_e32 v13, vcc, 0, v95, vcc
	v_add_co_u32_e32 v16, vcc, s38, v94
	v_lshl_add_u64 v[40:41], v[40:41], 0, v[90:91]
	s_nop 0
	v_addc_co_u32_e32 v17, vcc, 0, v95, vcc
	v_add_co_u32_e32 v20, vcc, s39, v94
	s_add_u32 s0, s33, s0
	s_nop 0
	v_addc_co_u32_e32 v21, vcc, 0, v95, vcc
	v_lshl_add_u64 v[42:43], v[40:41], 0, s[12:13]
	v_add_co_u32_e32 v40, vcc, s40, v40
	s_addc_u32 s1, s96, s1
	global_load_dwordx4 v[8:11], v[8:9], off
	s_nop 0
	global_load_dwordx4 v[12:15], v[12:13], off
	s_nop 0
	global_load_dwordx4 v[16:19], v[16:17], off
	s_nop 0
	global_load_dwordx4 v[20:23], v[20:21], off
	v_addc_co_u32_e32 v41, vcc, 0, v41, vcc
	global_load_dword v102, v77, s[0:1]
	global_load_dwordx2 v[112:113], v[40:41], off
	global_load_dwordx2 v[110:111], v[42:43], off offset:32
	global_load_dwordx2 v[108:109], v[42:43], off offset:64
	global_load_dwordx2 v[106:107], v[42:43], off offset:96
	s_lshl_b32 s49, s3, 6
	s_cmpk_gt_u32 s20, 0xff
	s_cselect_b64 s[18:19], -1, 0
	s_lshl_b32 s47, s3, 12
	s_lshl_b32 s45, s46, 6
	s_lshl_b32 s10, s46, 7
	s_cmpk_lt_u32 s20, 0x100
	s_cselect_b64 s[20:21], -1, 0
	s_or_b32 s0, s22, s2
	s_or_b32 s22, s0, 8
	s_mul_hi_i32 s1, s0, 0xa000
	s_mul_i32 s0, s0, 0xa000
	v_lshlrev_b32_e32 v40, 6, v44
	v_lshlrev_b32_e32 v41, 1, v44
	s_mov_b32 s48, 0
	v_lshl_add_u64 v[96:97], v[82:83], 0, s[10:11]
	v_lshl_add_u64 v[98:99], v[84:85], 0, s[10:11]
	v_or_b32_e32 v137, s47, v103
	v_add_u32_e32 v138, v131, v41
	v_add_u32_e32 v139, v132, v41
	s_mov_b32 s50, 0
	s_waitcnt vmcnt(0)
	ds_write_b128 v133, v[24:27]
	ds_write_b128 v133, v[28:31] offset:9216
	ds_write_b128 v133, v[32:35] offset:18432
	ds_write_b128 v133, v[36:39] offset:27648
	v_or_b32_e32 v24, s0, v76
	v_mov_b32_e32 v25, s1
	v_lshl_add_u64 v[100:101], v[86:87], 0, v[24:25]
	s_mov_b32 s98, 0xfffaffc0
	s_mov_b32 s99, -1
	v_lshl_add_u64 v[214:215], v[100:101], 0, s[98:99]
	s_mov_b32 s100, 0
	s_mul_i32 s98, s100, 0x50000
	s_mov_b32 s99, 0
	v_lshl_add_u64 v[216:217], v[214:215], 0, s[98:99]
	global_load_dwordx2 v[184:185], v[216:217], off
	global_load_dwordx2 v[186:187], v[216:217], off offset:32
	global_load_dwordx2 v[188:189], v[216:217], off offset:64
	global_load_dwordx2 v[190:191], v[216:217], off offset:96
	s_add_i32 s100, s100, s49
	s_lshl_b32 s100, s100, 3
	s_or_b32 s100, s100, s46
	s_lshl_b32 s100, s100, 2
	s_add_u32 s100, s33, s100
	s_addc_u32 s101, s96, 0
	global_load_dword v192, v77, s[100:101]
	s_mov_b32 s100, 1
	s_mul_i32 s98, s100, 0x50000
	s_mov_b32 s99, 0
	v_lshl_add_u64 v[216:217], v[214:215], 0, s[98:99]
	global_load_dwordx2 v[204:205], v[216:217], off
	global_load_dwordx2 v[206:207], v[216:217], off offset:32
	global_load_dwordx2 v[208:209], v[216:217], off offset:64
	global_load_dwordx2 v[210:211], v[216:217], off offset:96
	s_add_i32 s100, s100, s49
	s_lshl_b32 s100, s100, 3
	s_or_b32 s100, s100, s46
	s_lshl_b32 s100, s100, 2
	s_add_u32 s100, s33, s100
	s_addc_u32 s101, s96, 0
	global_load_dword v212, v77, s[100:101]
	s_mov_b32 s98, 0
	v_add_u32_e32 v216, s98, v137
	v_add_u32_e32 v218, 32, v216
	v_ashrrev_i32_e32 v217, 31, v216
	v_ashrrev_i32_e32 v219, 31, v218
	v_lshlrev_b64 v[216:217], 11, v[216:217]
	v_lshlrev_b64 v[218:219], 11, v[218:219]
	v_lshl_add_u64 v[216:217], v[96:97], 0, v[216:217]
	v_lshl_add_u64 v[218:219], v[96:97], 0, v[218:219]
	global_load_dwordx4 v[176:179], v[216:217], off
	global_load_dwordx4 v[180:183], v[218:219], off
	s_waitcnt vmcnt(0)
	s_mov_b64 s[0:1], 0
	v_lshlrev_b32_e32 v76, 1, v40
	v_mov_b32_e32 v24, v77
	v_mov_b32_e32 v25, v77
	v_mov_b32_e32 v26, v77
	v_mov_b32_e32 v27, v77
	v_mov_b32_e32 v28, v77
	v_mov_b32_e32 v29, v77
	v_mov_b32_e32 v30, v77
	v_mov_b32_e32 v31, v77
	v_mov_b32_e32 v32, v77
	v_mov_b32_e32 v33, v77
	v_mov_b32_e32 v34, v77
	v_mov_b32_e32 v35, v77
	v_mov_b32_e32 v36, v77
	v_mov_b32_e32 v37, v77
	v_mov_b32_e32 v38, v77
	v_mov_b32_e32 v39, v77
	s_waitcnt lgkmcnt(0)
	s_barrier
	s_branch .LBB0_820
.LBB0_819:
	s_add_i32 s50, s50, 2
	s_addk_i32 s48, 0x80
	s_add_i32 s22, s22, 16
	s_and_b64 vcc, exec, s[26:27]
	s_mov_b64 s[0:1], s[24:25]
	s_cmp_lg_u64 s[18:19], 0
	s_cbranch_scc1 .Lsc2_a_hi
	s_waitcnt vmcnt(11)
	s_branch .Lsc2_a_j
.Lsc2_a_hi:
	s_waitcnt vmcnt(13)
.Lsc2_a_j:
	ds_write_b128 v133, v[40:43]
	ds_write_b128 v133, v[44:47] offset:9216
	ds_write_b128 v133, v[48:51] offset:18432
	ds_write_b128 v133, v[52:55] offset:27648
	s_waitcnt lgkmcnt(0)
	s_barrier
	s_cbranch_vccnz .LBB0_830
; #define SC_ISSUE(P, n) do { const int nn_ = (n) < 64 ? (n) : 63; const unsigned char* Gn_ = G0 + (size_t)nn_ * (8 * 40960); _Pragma("unroll") for (int mt = 0; mt < 4; ++mt) P[mt] = __builtin_nontemporal_load((const u32x4*)(Gn_ + mt * 8192 + tid * 16)); } while (0)
; #define SC_GATE(n) do { const int nn_ = (n) < 64 ? (n) : 63; _Pragma("unroll") for (int pp_ = 0; pp_ < 2; ++pp_) gt[pp_] = __builtin_nontemporal_load((const u32x4*)(PSg + (size_t)(b * T + 64 * nn_ + fr0 + 32 * pp_) * 1024 + h * 64 + 8 * fc8)); } while (0)
; DI void gdn_scan(int b, int h, const unsigned char* G, const float* glast, const bf16* PSg, const float* g_gdn, bf16* MIXA, LAS unsigned char* lds, int tid) {
;     ...
;         SC_ISSUE(pA, n + 2);
;         if (n > 0) SC_FLUSH(n - 1, 1);
;         SC_GATE(n);
.LBB0_820:
	v_mov_b64_e32 v[60:61], v[168:169]
	v_mov_b64_e32 v[62:63], v[170:171]
	v_mov_b64_e32 v[56:57], v[172:173]
	v_mov_b64_e32 v[58:59], v[174:175]
	v_mov_b64_e32 v[112:113], v[184:185]
	v_mov_b64_e32 v[110:111], v[186:187]
	v_mov_b64_e32 v[108:109], v[188:189]
	v_mov_b64_e32 v[106:107], v[190:191]
	v_mov_b32_e32 v102, v192
	s_add_i32 s98, s50, 1
	s_lshl_b32 s98, s98, 6
	v_add_u32_e32 v216, s98, v137
	v_add_u32_e32 v218, 32, v216
	v_ashrrev_i32_e32 v217, 31, v216
	v_ashrrev_i32_e32 v219, 31, v218
	v_lshlrev_b64 v[216:217], 11, v[216:217]
	v_lshlrev_b64 v[218:219], 11, v[218:219]
	v_lshl_add_u64 v[216:217], v[96:97], 0, v[216:217]
	v_lshl_add_u64 v[218:219], v[96:97], 0, v[218:219]
	global_load_dwordx4 v[168:171], v[216:217], off
	global_load_dwordx4 v[172:175], v[218:219], off
	s_add_i32 s100, s50, 2
	s_min_u32 s100, s100, 63
	s_mul_i32 s98, s100, 0x50000
	s_mov_b32 s99, 0
	v_lshl_add_u64 v[216:217], v[214:215], 0, s[98:99]
	global_load_dwordx2 v[184:185], v[216:217], off
	global_load_dwordx2 v[186:187], v[216:217], off offset:32
	global_load_dwordx2 v[188:189], v[216:217], off offset:64
	global_load_dwordx2 v[190:191], v[216:217], off offset:96
	s_add_i32 s100, s100, s49
	s_lshl_b32 s100, s100, 3
	s_or_b32 s100, s100, s46
	s_lshl_b32 s100, s100, 2
	s_add_u32 s100, s33, s100
	s_addc_u32 s101, s96, 0
	global_load_dword v192, v77, s[100:101]
	s_cmp_gt_u32 s50, 61
	s_cselect_b64 s[26:27], -1, 0
	s_add_u32 s24, s0, 0xa0000
	s_addc_u32 s25, s1, 0
	s_cmp_lt_u32 s50, 62
	s_cselect_b32 s10, s24, 0x13b0000
	v_lshl_add_u64 v[48:49], v[94:95], 0, s[10:11]
	v_add_co_u32_e32 v44, vcc, s31, v48
	s_cmp_lg_u32 s48, 0
	s_nop 0
	v_addc_co_u32_e32 v45, vcc, 0, v49, vcc
	v_add_co_u32_e32 v50, vcc, 0x4000, v48
	global_load_dwordx4 v[40:43], v[48:49], off
	s_nop 0
	global_load_dwordx4 v[44:47], v[44:45], off
	v_addc_co_u32_e32 v51, vcc, 0, v49, vcc
	v_add_co_u32_e32 v52, vcc, 0x6000, v48
	s_cselect_b64 s[2:3], -1, 0
	s_nop 0
	v_addc_co_u32_e32 v53, vcc, 0, v49, vcc
	global_load_dwordx4 v[48:51], v[50:51], off
	s_nop 0
	global_load_dwordx4 v[52:55], v[52:53], off
	s_and_b64 s[52:53], s[2:3], s[18:19]
	s_mov_b64 s[2:3], -1
	s_and_b64 vcc, exec, s[52:53]
	v_add_u32_e32 v64, s48, v137
	s_cbranch_vccnz .LBB0_822
	v_add_u32_e32 v122, s48, v137
	s_mov_b64 s[2:3], 0
.LBB0_822:
	s_andn2_b64 vcc, exec, s[2:3]
	s_cbranch_vccnz .LBB0_824
	v_and_b32_e32 v66, 64, v136
	v_xor_b32_e32 v65, 1, v136
	v_add_u32_e32 v70, 64, v66
	v_cmp_lt_i32_e32 vcc, v65, v70
	v_xor_b32_e32 v66, 2, v136
	v_add_u32_e32 v72, v105, v128
	v_cndmask_b32_e32 v65, v136, v65, vcc
	v_cmp_lt_i32_e32 vcc, v66, v70
	s_nop 0
	v_lshlrev_b32_e32 v122, 16, v61
	v_and_b32_e32 v123, 0xffff0000, v61
	v_cndmask_b32_e32 v66, v136, v66, vcc
	v_lshlrev_b32_e32 v89, 2, v66
	ds_read_b128 v[66:69], v72
	v_mul_f32_e32 v61, 0xbfb8aa3b, v122
	v_exp_f32_e32 v61, v61
	v_mul_f32_e32 v124, 0xbfb8aa3b, v123
	v_exp_f32_e32 v124, v124
	s_waitcnt lgkmcnt(0)
	v_lshlrev_b32_e32 v118, 16, v68
	v_and_b32_e32 v119, 0xffff0000, v68
	v_lshlrev_b32_e32 v68, 16, v62
	v_lshlrev_b32_e32 v74, 16, v69
	v_and_b32_e32 v75, 0xffff0000, v69
	v_and_b32_e32 v69, 0xffff0000, v62
	v_mul_f32_e32 v62, 0xbfb8aa3b, v68
	v_exp_f32_e32 v120, v62
	v_mul_f32_e32 v62, 0xbfb8aa3b, v69
	v_exp_f32_e32 v121, v62
	v_add_f32_e32 v61, 1.0, v61
	v_add_f32_e32 v120, 1.0, v120
	v_rcp_f32_e32 v120, v120
	v_add_f32_e32 v121, 1.0, v121
	v_rcp_f32_e32 v121, v121
	v_and_b32_e32 v125, 0xffff0000, v67
	v_lshlrev_b32_e32 v114, 16, v63
	v_and_b32_e32 v115, 0xffff0000, v63
	v_pk_mul_f32 v[68:69], v[120:121], v[68:69]
	v_rcp_f32_e32 v120, v61
	v_add_f32_e32 v61, 1.0, v124
	v_rcp_f32_e32 v121, v61
	v_lshlrev_b32_e32 v124, 16, v67
	v_xor_b32_e32 v71, 4, v136
	v_mul_f32_e32 v141, 0xbfb8aa3b, v115
	v_pk_mul_f32 v[120:121], v[120:121], v[122:123]
	v_lshlrev_b32_e32 v122, 16, v60
	v_and_b32_e32 v123, 0xffff0000, v60
	v_mul_f32_e32 v60, 0xbfb8aa3b, v122
	v_exp_f32_e32 v61, v60
	v_mul_f32_e32 v60, 0xbfb8aa3b, v123
	v_exp_f32_e32 v67, v60
	v_cmp_lt_i32_e32 vcc, v71, v70
	v_add_f32_e32 v61, 1.0, v61
	v_rcp_f32_e32 v140, v61
	v_add_f32_e32 v61, 1.0, v67
	v_mul_f32_e32 v67, 0xbfb8aa3b, v114
	v_exp_f32_e32 v67, v67
	v_exp_f32_e32 v143, v141
	v_cndmask_b32_e32 v70, v136, v71, vcc
	v_lshlrev_b32_e32 v104, 2, v70
	ds_read_b128 v[70:73], v72 offset:4608
	v_rcp_f32_e32 v141, v61
	v_add_f32_e32 v61, 1.0, v67
	v_rcp_f32_e32 v142, v61
	v_add_f32_e32 v61, 1.0, v143
	v_rcp_f32_e32 v143, v61
	s_nop 0
	v_lshlrev_b32_e32 v154, 16, v57
	v_lshlrev_b32_e32 v60, 16, v66
	v_and_b32_e32 v61, 0xffff0000, v66
	v_mul_f32_e32 v153, 0xbfb8aa3b, v154
	s_waitcnt lgkmcnt(0)
	v_lshlrev_b32_e32 v162, 16, v70
	v_and_b32_e32 v163, 0xffff0000, v70
	v_pk_mul_f32 v[66:67], v[60:61], v[60:61]
	v_lshlrev_b32_e32 v148, 16, v72
	v_and_b32_e32 v149, 0xffff0000, v72
	v_lshlrev_b32_e32 v72, 16, v58
	v_lshlrev_b32_e32 v152, 16, v71
	v_exp_f32_e32 v159, v153
	v_and_b32_e32 v153, 0xffff0000, v71
	v_pk_mul_f32 v[70:71], v[162:163], v[162:163]
	v_pk_mul_f32 v[126:127], v[124:125], v[124:125]
	v_pk_mul_f32 v[114:115], v[142:143], v[114:115]
	v_lshlrev_b32_e32 v142, 16, v73
	v_and_b32_e32 v143, 0xffff0000, v73
	v_and_b32_e32 v73, 0xffff0000, v58
	v_mul_f32_e32 v58, 0xbfb8aa3b, v72
	v_pk_mul_f32 v[156:157], v[152:153], v[152:153]
	v_mov_b32_e32 v164, v70
	v_mov_b32_e32 v165, v66
	v_mov_b32_e32 v66, v71
	v_exp_f32_e32 v150, v58
	v_mul_f32_e32 v58, 0xbfb8aa3b, v73
	v_pk_add_f32 v[66:67], v[164:165], v[66:67]
	v_mov_b32_e32 v70, v156
	v_mov_b32_e32 v71, v126
	v_pk_mul_f32 v[62:63], v[118:119], v[118:119]
	v_lshlrev_b32_e32 v144, 16, v59
	v_and_b32_e32 v145, 0xffff0000, v59
	v_exp_f32_e32 v151, v58
	v_pk_mul_f32 v[58:59], v[148:149], v[148:149]
	v_pk_add_f32 v[66:67], v[70:71], v[66:67]
	v_mov_b32_e32 v126, v157
	v_pk_add_f32 v[66:67], v[126:127], v[66:67]
	v_mov_b32_e32 v70, v58
	v_mov_b32_e32 v71, v62
	v_pk_mul_f32 v[116:117], v[74:75], v[74:75]
	v_pk_mul_f32 v[146:147], v[142:143], v[142:143]
	v_pk_add_f32 v[66:67], v[70:71], v[66:67]
	v_mov_b32_e32 v62, v59
	v_pk_add_f32 v[58:59], v[62:63], v[66:67]
	v_mov_b32_e32 v62, v146
	v_mov_b32_e32 v63, v116
	v_and_b32_e32 v155, 0xffff0000, v57
	v_add_f32_e32 v57, 1.0, v159
	v_pk_add_f32 v[58:59], v[62:63], v[58:59]
	v_mov_b32_e32 v116, v147
	v_lshlrev_b32_e32 v65, 2, v65
	v_rcp_f32_e32 v160, v57
	v_mul_f32_e32 v57, 0xbfb8aa3b, v155
	v_pk_add_f32 v[58:59], v[116:117], v[58:59]
	v_exp_f32_e32 v57, v57
	ds_bpermute_b32 v63, v65, v59
	ds_bpermute_b32 v62, v65, v58
	v_lshlrev_b32_e32 v66, 16, v56
	v_add_f32_e32 v57, 1.0, v57
	v_rcp_f32_e32 v161, v57
	v_and_b32_e32 v67, 0xffff0000, v56
	s_waitcnt lgkmcnt(0)
	v_pk_add_f32 v[56:57], v[58:59], v[62:63]
	ds_bpermute_b32 v59, v89, v57
	ds_bpermute_b32 v58, v89, v56
	v_mul_f32_e32 v62, 0xbfb8aa3b, v66
	v_mul_f32_e32 v63, 0xbfb8aa3b, v67
	v_exp_f32_e32 v62, v62
	v_exp_f32_e32 v63, v63
	s_waitcnt lgkmcnt(0)
	v_pk_add_f32 v[56:57], v[56:57], v[58:59]
	ds_bpermute_b32 v59, v104, v57
	ds_bpermute_b32 v58, v104, v56
	v_add_f32_e32 v62, 1.0, v62
	v_add_f32_e32 v63, 1.0, v63
	v_rcp_f32_e32 v62, v62
	v_rcp_f32_e32 v63, v63
	s_waitcnt lgkmcnt(0)
	v_pk_add_f32 v[56:57], v[56:57], v[58:59]
	v_pk_mul_f32 v[122:123], v[140:141], v[122:123]
	v_pk_fma_f32 v[58:59], v[56:57], s[14:15], v[92:93] op_sel_hi:[1,0,0]
	v_pk_mul_f32 v[62:63], v[62:63], v[66:67]
	v_mul_f32_e32 v56, 0x4b800000, v59
	v_cmp_gt_f32_e32 vcc, s41, v59
	v_subrev_u32_e32 v140, 64, v64
	v_ashrrev_i32_e32 v141, 31, v140
	v_cndmask_b32_e32 v56, v59, v56, vcc
	v_rsq_f32_e32 v56, v56
	v_mul_f32_e32 v59, 0x4b800000, v58
	v_lshlrev_b64 v[140:141], 11, v[140:141]
	v_lshl_add_u64 v[140:141], v[98:99], 0, v[140:141]
	v_mul_f32_e32 v57, 0x45800000, v56
	v_cndmask_b32_e32 v56, v56, v57, vcc
	v_pk_mul_f32 v[60:61], v[56:57], v[60:61] op_sel_hi:[0,1]
	v_pk_mul_f32 v[60:61], v[4:5], v[60:61]
	v_pk_mul_f32 v[66:67], v[56:57], v[124:125] op_sel_hi:[0,1]
	v_pk_mul_f32 v[116:117], v[56:57], v[118:119] op_sel_hi:[0,1]
	v_pk_mul_f32 v[56:57], v[56:57], v[74:75] op_sel_hi:[0,1]
	v_cmp_gt_f32_e32 vcc, s41, v58
	v_pk_mul_f32 v[60:61], v[122:123], v[60:61]
	v_pk_mul_f32 v[56:57], v[2:3], v[56:57]
	v_cndmask_b32_e32 v58, v58, v59, vcc
	v_pk_mul_f32 v[74:75], v[114:115], v[56:57]
	v_cvt_pk_bf16_f32 v56, v60, v61
	v_rsq_f32_e32 v60, v58
	v_pk_mul_f32 v[66:67], v[6:7], v[66:67]
	v_pk_mul_f32 v[116:117], v[0:1], v[116:117]
	v_pk_mul_f32 v[66:67], v[120:121], v[66:67]
	v_pk_mul_f32 v[68:69], v[68:69], v[116:117]
	v_cvt_pk_bf16_f32 v57, v66, v67
	v_cvt_pk_bf16_f32 v58, v68, v69
	v_cvt_pk_bf16_f32 v59, v74, v75
	global_store_dwordx4 v[140:141], v[56:59], off offset:1024
	v_mul_f32_e32 v65, 0xbfb8aa3b, v145
	v_exp_f32_e32 v65, v65
	v_mul_f32_e32 v56, 0x45800000, v60
	v_cndmask_b32_e32 v56, v60, v56, vcc
	v_pk_mul_f32 v[58:59], v[56:57], v[162:163] op_sel_hi:[0,1]
	v_pk_mul_f32 v[58:59], v[4:5], v[58:59]
	v_pk_mul_f32 v[60:61], v[56:57], v[152:153] op_sel_hi:[0,1]
	v_pk_mul_f32 v[58:59], v[62:63], v[58:59]
	v_pk_mul_f32 v[62:63], v[56:57], v[148:149] op_sel_hi:[0,1]
	v_mul_f32_e32 v57, 0xbfb8aa3b, v144
	v_exp_f32_e32 v57, v57
	v_add_f32_e32 v150, 1.0, v150
	v_add_f32_e32 v151, 1.0, v151
	v_rcp_f32_e32 v150, v150
	v_add_f32_e32 v57, 1.0, v57
	v_rcp_f32_e32 v151, v151
	v_rcp_f32_e32 v66, v57
	v_add_f32_e32 v57, 1.0, v65
	v_rcp_f32_e32 v67, v57
	v_pk_mul_f32 v[70:71], v[150:151], v[72:73]
	v_pk_mul_f32 v[72:73], v[160:161], v[154:155]
	v_pk_mul_f32 v[60:61], v[6:7], v[60:61]
	v_pk_mul_f32 v[56:57], v[56:57], v[142:143] op_sel_hi:[0,1]
	v_pk_mul_f32 v[60:61], v[72:73], v[60:61]
	v_pk_mul_f32 v[56:57], v[2:3], v[56:57]
	v_pk_mul_f32 v[66:67], v[66:67], v[144:145]
	v_pk_mul_f32 v[62:63], v[0:1], v[62:63]
	v_pk_mul_f32 v[66:67], v[66:67], v[56:57]
	v_cvt_pk_bf16_f32 v57, v60, v61
	v_subrev_u32_e32 v60, 32, v64
	v_ashrrev_i32_e32 v61, 31, v60
	v_pk_mul_f32 v[62:63], v[70:71], v[62:63]
	v_lshlrev_b64 v[60:61], 11, v[60:61]
	v_cvt_pk_bf16_f32 v56, v58, v59
	v_cvt_pk_bf16_f32 v58, v62, v63
	v_cvt_pk_bf16_f32 v59, v66, v67
	v_lshl_add_u64 v[60:61], v[98:99], 0, v[60:61]
	v_mov_b32_e32 v122, v64
	global_store_dwordx4 v[60:61], v[56:59], off offset:1024
.LBB0_824:
	s_nop 0
	s_nop 0
	v_add_u32_e32 v58, 32, v122
	v_ashrrev_i32_e32 v123, 31, v122
	v_ashrrev_i32_e32 v59, 31, v58
	v_lshlrev_b64 v[126:127], 11, v[122:123]
	v_lshlrev_b64 v[124:125], 11, v[58:59]
	s_ashr_i32 s23, s22, 31
	v_lshl_add_u64 v[56:57], v[96:97], 0, v[126:127]
	v_lshl_add_u64 v[58:59], v[96:97], 0, v[124:125]
	v_lshl_add_u64 v[64:65], v[100:101], 0, s[0:1]
	s_lshl_b64 s[0:1], s[22:23], 2
	s_nop 0
	s_nop 0
	s_add_u32 s0, s33, s0
	s_addc_u32 s1, s96, s1
	v_cndmask_b32_e64 v64, 0, 1, s[20:21]
	v_cmp_ne_u32_e64 s[0:1], 1, v64
	s_andn2_b64 vcc, exec, s[20:21]
	s_cbranch_vccnz .LBB0_826
	ds_read2_b64 v[144:147], v130 offset1:4
	v_add_u32_e32 v75, 0x800, v130
	ds_read2_b64 v[152:155], v75 offset0:32 offset1:36
	s_nop 0
	v_lshlrev_b32_e32 v140, 16, v112
	v_and_b32_e32 v141, 0xffff0000, v112
	v_lshlrev_b32_e32 v142, 16, v113
	v_and_b32_e32 v143, 0xffff0000, v113
	v_cvt_pk_bf16_f32 v68, v24, v25
	v_cvt_pk_bf16_f32 v69, v26, v27
	v_cvt_pk_bf16_f32 v70, v28, v29
	v_cvt_pk_bf16_f32 v71, v30, v31
	ds_read2_b64 v[148:151], v130 offset0:8 offset1:12
	v_add_u32_e32 v89, 0x1000, v130
	s_waitcnt lgkmcnt(2)
	v_mfma_f32_16x16x32_bf16 v[140:143], v[144:147], v[68:71], v[140:143]
	ds_read2_b64 v[144:147], v75 offset0:40 offset1:44
	s_nop 0
	v_lshlrev_b32_e32 v72, 16, v110
	v_and_b32_e32 v73, 0xffff0000, v110
	v_lshlrev_b32_e32 v74, 16, v111
	v_and_b32_e32 v75, 0xffff0000, v111
	ds_read2_b64 v[110:113], v89 offset0:64 offset1:68
	v_cvt_pk_bf16_f32 v64, v32, v33
	s_waitcnt lgkmcnt(3)
	v_mfma_f32_16x16x32_bf16 v[72:75], v[152:155], v[68:71], v[72:75]
	v_cvt_pk_bf16_f32 v65, v34, v35
	v_cvt_pk_bf16_f32 v66, v36, v37
	v_cvt_pk_bf16_f32 v67, v38, v39
	s_nop 0
	v_lshlrev_b32_e32 v152, 16, v106
	v_and_b32_e32 v153, 0xffff0000, v106
	s_waitcnt lgkmcnt(2)
	v_mfma_f32_16x16x32_bf16 v[140:143], v[148:151], v[64:67], v[140:143]
	v_lshlrev_b32_e32 v148, 16, v108
	v_and_b32_e32 v149, 0xffff0000, v108
	v_lshlrev_b32_e32 v150, 16, v109
	s_waitcnt lgkmcnt(1)
	v_mfma_f32_16x16x32_bf16 v[144:147], v[144:147], v[64:67], v[72:75]
	v_and_b32_e32 v151, 0xffff0000, v109
	v_lshlrev_b32_e32 v154, 16, v107
	v_and_b32_e32 v155, 0xffff0000, v107
	ds_read2_b64 v[72:75], v89 offset0:72 offset1:76
	v_add_u32_e32 v89, 0x1800, v130
	s_waitcnt lgkmcnt(1)
	v_mfma_f32_16x16x32_bf16 v[108:111], v[110:113], v[68:71], v[148:151]
	ds_read2_b64 v[160:163], v89 offset0:104 offset1:108
	v_add_u32_e32 v106, 0x4800, v130
	v_add_u32_e32 v123, 0x5000, v130
	ds_read2_b64 v[148:151], v89 offset0:96 offset1:100
	v_add_u32_e32 v89, 0x2000, v130
	s_waitcnt lgkmcnt(2)
	v_mfma_f32_16x16x32_bf16 v[108:111], v[72:75], v[64:67], v[108:111]
	s_nop 0
	v_pk_mul_f32 v[26:27], v[102:103], v[26:27] op_sel_hi:[0,1]
	v_pk_mul_f32 v[24:25], v[102:103], v[24:25] op_sel_hi:[0,1]
	v_pk_mul_f32 v[30:31], v[102:103], v[30:31] op_sel_hi:[0,1]
	s_waitcnt lgkmcnt(0)
	v_mfma_f32_16x16x32_bf16 v[72:75], v[148:151], v[68:71], v[152:155]
	ds_read2_b64 v[148:151], v89 offset0:128 offset1:132
	s_nop 0
	v_cvt_pk_bf16_f32 v107, v110, v111
	v_pk_mul_f32 v[28:29], v[102:103], v[28:29] op_sel_hi:[0,1]
	v_mfma_f32_16x16x32_bf16 v[152:155], v[160:163], v[64:67], v[72:75]
	ds_read2_b64 v[160:163], v106 offset1:4
	v_pk_mul_f32 v[34:35], v[102:103], v[34:35] op_sel_hi:[0,1]
	v_pk_mul_f32 v[32:33], v[102:103], v[32:33] op_sel_hi:[0,1]
	v_cvt_pk_bf16_f32 v72, v140, v141
	v_cvt_pk_bf16_f32 v73, v142, v143
	s_waitcnt lgkmcnt(1)
	v_mfma_f32_16x16x32_bf16 v[140:143], v[148:151], v[68:71], 0
	ds_read2_b64 v[148:151], v89 offset0:136 offset1:140
	v_cvt_pk_bf16_f32 v74, v144, v145
	v_cvt_pk_bf16_f32 v75, v146, v147
	ds_read2_b64 v[144:147], v106 offset0:8 offset1:12
	v_cvt_pk_bf16_f32 v106, v108, v109
	s_waitcnt lgkmcnt(2)
	v_mfma_f32_16x16x32_bf16 v[140:143], v[160:163], v[72:75], v[140:143]
	v_cvt_pk_bf16_f32 v108, v152, v153
	v_cvt_pk_bf16_f32 v109, v154, v155
	v_pk_mul_f32 v[38:39], v[102:103], v[38:39] op_sel_hi:[0,1]
	s_waitcnt lgkmcnt(1)
	v_mfma_f32_16x16x32_bf16 v[140:143], v[148:151], v[64:67], v[140:143]
	v_mul_f32_e64 v36, v102, v36
	v_mul_f32_e64 v37, v102, v37
	s_waitcnt lgkmcnt(0)
	v_mfma_f32_16x16x32_bf16 v[110:113], v[144:147], v[106:109], v[140:143]
	s_nop 7
	v_cvt_pk_bf16_f32 v89, v110, s0
	ds_write_b16 v138, v89
	v_cvt_pk_bf16_f32 v89, v111, s0
	ds_write_b16 v138, v89 offset:144
	v_cvt_pk_bf16_f32 v89, v112, s0
	ds_write_b16 v138, v89 offset:288
	v_cvt_pk_bf16_f32 v89, v113, s0
	ds_write_b16 v138, v89 offset:432
	v_add_u32_e32 v89, 0x2800, v130
	ds_read2_b64 v[110:113], v89 offset0:160 offset1:164
	ds_read2_b64 v[140:143], v123 offset0:32 offset1:36
	s_waitcnt lgkmcnt(1)
	v_mfma_f32_16x16x32_bf16 v[110:113], v[110:113], v[68:71], 0
	s_waitcnt lgkmcnt(0)
	v_mfma_f32_16x16x32_bf16 v[110:113], v[140:143], v[72:75], v[110:113]
	ds_read2_b64 v[140:143], v89 offset0:168 offset1:172
	s_waitcnt lgkmcnt(0)
	v_mfma_f32_16x16x32_bf16 v[110:113], v[140:143], v[64:67], v[110:113]
	ds_read2_b64 v[140:143], v123 offset0:40 offset1:44
	v_add_u32_e32 v123, 0x5800, v130
	s_waitcnt lgkmcnt(0)
	v_mfma_f32_16x16x32_bf16 v[110:113], v[140:143], v[106:109], v[110:113]
	s_nop 7
	v_cvt_pk_bf16_f32 v89, v110, s0
	ds_write_b16 v138, v89 offset:2304
	v_cvt_pk_bf16_f32 v89, v111, s0
	ds_write_b16 v138, v89 offset:2448
	v_cvt_pk_bf16_f32 v89, v112, s0
	ds_write_b16 v138, v89 offset:2592
	v_cvt_pk_bf16_f32 v89, v113, s0
	ds_write_b16 v138, v89 offset:2736
	v_add_u32_e32 v89, 0x3000, v130
	ds_read2_b64 v[110:113], v89 offset0:192 offset1:196
	ds_read2_b64 v[140:143], v123 offset0:64 offset1:68
	s_waitcnt lgkmcnt(1)
	v_mfma_f32_16x16x32_bf16 v[110:113], v[110:113], v[68:71], 0
	s_waitcnt lgkmcnt(0)
	v_mfma_f32_16x16x32_bf16 v[110:113], v[140:143], v[72:75], v[110:113]
	ds_read2_b64 v[140:143], v89 offset0:200 offset1:204
	s_waitcnt lgkmcnt(0)
	v_mfma_f32_16x16x32_bf16 v[110:113], v[140:143], v[64:67], v[110:113]
	ds_read2_b64 v[140:143], v123 offset0:72 offset1:76
	v_add_u32_e32 v123, 0x6000, v130
	s_waitcnt lgkmcnt(0)
	v_mfma_f32_16x16x32_bf16 v[110:113], v[140:143], v[106:109], v[110:113]
	s_nop 7
	v_cvt_pk_bf16_f32 v89, v110, s0
	ds_write_b16 v138, v89 offset:4608
	v_cvt_pk_bf16_f32 v89, v111, s0
	ds_write_b16 v138, v89 offset:4752
	v_cvt_pk_bf16_f32 v89, v112, s0
	ds_write_b16 v138, v89 offset:4896
	v_cvt_pk_bf16_f32 v89, v113, s0
	ds_write_b16 v138, v89 offset:5040
	v_add_u32_e32 v89, 0x3800, v130
	ds_read2_b64 v[110:113], v89 offset0:224 offset1:228
	s_waitcnt lgkmcnt(0)
	v_mfma_f32_16x16x32_bf16 v[68:71], v[110:113], v[68:71], 0
	ds_read2_b64 v[110:113], v123 offset0:96 offset1:100
	s_waitcnt lgkmcnt(0)
	v_mfma_f32_16x16x32_bf16 v[68:71], v[110:113], v[72:75], v[68:71]
	ds_read2_b64 v[110:113], v89 offset0:232 offset1:236
	s_waitcnt lgkmcnt(0)
	v_mfma_f32_16x16x32_bf16 v[64:67], v[110:113], v[64:67], v[68:71]
	s_nop 4
	ds_read2_b64 v[68:71], v123 offset0:104 offset1:108
	s_waitcnt lgkmcnt(0)
	v_mfma_f32_16x16x32_bf16 v[64:67], v[68:71], v[106:109], v[64:67]
	v_add_u32_e32 v68, 0x6800, v130
	s_nop 6
	v_cvt_pk_bf16_f32 v64, v64, s0
	ds_write_b16 v138, v64 offset:6912
	v_cvt_pk_bf16_f32 v64, v65, s0
	ds_write_b16 v138, v64 offset:7056
	v_cvt_pk_bf16_f32 v64, v66, s0
	ds_write_b16 v138, v64 offset:7200
	v_cvt_pk_bf16_f32 v64, v67, s0
	ds_write_b16 v138, v64 offset:7344
	ds_read2_b64 v[64:67], v68 offset0:128 offset1:132
	s_waitcnt lgkmcnt(0)
	v_mfma_f32_16x16x32_bf16 v[24:27], v[64:67], v[72:75], v[24:27]
	ds_read2_b64 v[64:67], v68 offset0:136 offset1:140
	v_add_u32_e32 v68, 0x7000, v130
	s_waitcnt lgkmcnt(0)
	v_mfma_f32_16x16x32_bf16 v[24:27], v[64:67], v[106:109], v[24:27]
	ds_read2_b64 v[64:67], v68 offset0:160 offset1:164
	s_waitcnt lgkmcnt(0)
	v_mfma_f32_16x16x32_bf16 v[28:31], v[64:67], v[72:75], v[28:31]
	ds_read2_b64 v[64:67], v68 offset0:168 offset1:172
	v_add_u32_e32 v68, 0x7800, v130
	s_waitcnt lgkmcnt(0)
	v_mfma_f32_16x16x32_bf16 v[28:31], v[64:67], v[106:109], v[28:31]
	ds_read2_b64 v[64:67], v68 offset0:192 offset1:196
	s_waitcnt lgkmcnt(0)
	v_mfma_f32_16x16x32_bf16 v[32:35], v[64:67], v[72:75], v[32:35]
	ds_read2_b64 v[64:67], v68 offset0:200 offset1:204
	v_add_u32_e32 v68, 0x8000, v130
	s_waitcnt lgkmcnt(0)
	v_mfma_f32_16x16x32_bf16 v[32:35], v[64:67], v[106:109], v[32:35]
	ds_read2_b64 v[64:67], v68 offset0:224 offset1:228
	s_waitcnt lgkmcnt(0)
	v_mfma_f32_16x16x32_bf16 v[36:39], v[64:67], v[72:75], v[36:39]
	ds_read2_b64 v[64:67], v68 offset0:232 offset1:236
	s_waitcnt lgkmcnt(0)
	v_mfma_f32_16x16x32_bf16 v[36:39], v[64:67], v[106:109], v[36:39]
; #define SC_ISSUE(P, n) do { const int nn_ = (n) < 64 ? (n) : 63; const unsigned char* Gn_ = G0 + (size_t)nn_ * (8 * 40960); _Pragma("unroll") for (int mt = 0; mt < 4; ++mt) P[mt] = __builtin_nontemporal_load((const u32x4*)(Gn_ + mt * 8192 + tid * 16)); } while (0)
; #define SC_COMMIT(P, stage) do { LAS unsigned char* nb_ = lds + (stage) * 36864; _Pragma("unroll") for (int mt = 0; mt < 4; ++mt) *(LAS u32x4*)(nb_ + mt * 9216 + prow * 144 + pc * 16) = P[mt]; } while (0)
; #define SC_GATE(n) do { const int nn_ = (n) < 64 ? (n) : 63; _Pragma("unroll") for (int pp_ = 0; pp_ < 2; ++pp_) gt[pp_] = __builtin_nontemporal_load((const u32x4*)(PSg + (size_t)(b * T + 64 * nn_ + fr0 + 32 * pp_) * 1024 + h * 64 + 8 * fc8)); } while (0)
; DI void gdn_scan(int b, int h, const unsigned char* G, const float* glast, const bf16* PSg, const float* g_gdn, bf16* MIXA, LAS unsigned char* lds, int tid) {
;     ...
;         SC_COMMIT(pB, 1);
;         __syncthreads();
;         SC_ISSUE(pB, n + 3);
;         SC_FLUSH(n, 0);
;         SC_GATE(n + 1);
;         SC_COMPUTE(n + 1, 1);
.LBB0_826:
	s_cmp_lg_u64 s[18:19], 0
	s_cbranch_scc1 .Lsc2_b_hi
	s_waitcnt vmcnt(11)
	s_branch .Lsc2_b_j
.Lsc2_b_hi:
	s_waitcnt vmcnt(15)
.Lsc2_b_j:
	s_min_u32 s2, s50, 60
	s_mul_i32 s2, s2, 0x50000
	s_add_u32 s2, s16, s2
	s_addc_u32 s3, s17, 0
	ds_write_b128 v133, v[8:11] offset:36864
	ds_write_b128 v133, v[12:15] offset:46080
	ds_write_b128 v133, v[16:19] offset:55296
	ds_write_b128 v133, v[20:23] offset:64512
	v_lshl_add_u64 v[16:17], s[2:3], 0, v[80:81]
	v_add_co_u32_e32 v8, vcc, s42, v16
	s_waitcnt lgkmcnt(0)
	s_nop 0
	v_addc_co_u32_e32 v9, vcc, 0, v17, vcc
	v_add_co_u32_e32 v12, vcc, 0xf2000, v16
	s_barrier
	v_mov_b64_e32 v[60:61], v[176:177]
	v_mov_b64_e32 v[62:63], v[178:179]
	v_mov_b64_e32 v[56:57], v[180:181]
	v_mov_b64_e32 v[58:59], v[182:183]
	v_mov_b64_e32 v[120:121], v[204:205]
	v_mov_b64_e32 v[118:119], v[206:207]
	v_mov_b64_e32 v[116:117], v[208:209]
	v_mov_b64_e32 v[114:115], v[210:211]
	v_mov_b32_e32 v104, v212
	s_add_i32 s98, s50, 2
	s_min_u32 s98, s98, 63
	s_lshl_b32 s98, s98, 6
	v_add_u32_e32 v216, s98, v137
	v_add_u32_e32 v218, 32, v216
	v_ashrrev_i32_e32 v217, 31, v216
	v_ashrrev_i32_e32 v219, 31, v218
	v_lshlrev_b64 v[216:217], 11, v[216:217]
	v_lshlrev_b64 v[218:219], 11, v[218:219]
	v_lshl_add_u64 v[216:217], v[96:97], 0, v[216:217]
	v_lshl_add_u64 v[218:219], v[96:97], 0, v[218:219]
	global_load_dwordx4 v[176:179], v[216:217], off
	global_load_dwordx4 v[180:183], v[218:219], off
	s_add_i32 s100, s50, 3
	s_min_u32 s100, s100, 63
	s_mul_i32 s98, s100, 0x50000
	s_mov_b32 s99, 0
	v_lshl_add_u64 v[216:217], v[214:215], 0, s[98:99]
	global_load_dwordx2 v[204:205], v[216:217], off
	global_load_dwordx2 v[206:207], v[216:217], off offset:32
	global_load_dwordx2 v[208:209], v[216:217], off offset:64
	global_load_dwordx2 v[210:211], v[216:217], off offset:96
	s_add_i32 s100, s100, s49
	s_lshl_b32 s100, s100, 3
	s_or_b32 s100, s100, s46
	s_lshl_b32 s100, s100, 2
	s_add_u32 s100, s33, s100
	s_addc_u32 s101, s96, 0
	global_load_dword v212, v77, s[100:101]
	s_nop 0
	v_addc_co_u32_e32 v13, vcc, 0, v17, vcc
	v_add_co_u32_e32 v18, vcc, 0xf4000, v16
	s_nop 1
	v_addc_co_u32_e32 v19, vcc, 0, v17, vcc
	v_add_co_u32_e32 v20, vcc, 0xf6000, v16
	global_load_dwordx4 v[8:11], v[8:9], off
	s_nop 0
	global_load_dwordx4 v[12:15], v[12:13], off
	v_addc_co_u32_e32 v21, vcc, 0, v17, vcc
	global_load_dwordx4 v[16:19], v[18:19], off
	s_nop 0
	global_load_dwordx4 v[20:23], v[20:21], off
	v_cndmask_b32_e64 v64, 0, 1, s[18:19]
	v_cmp_ne_u32_e64 s[2:3], 1, v64
	s_andn2_b64 vcc, exec, s[18:19]
	s_cbranch_vccnz .LBB0_828
	v_and_b32_e32 v65, 64, v136
	v_xor_b32_e32 v64, 1, v136
	v_add_u32_e32 v68, 64, v65
	v_cmp_lt_i32_e32 vcc, v64, v68
	v_xor_b32_e32 v69, 4, v136
	s_nop 0
	v_lshlrev_b32_e32 v112, 16, v61
	v_cndmask_b32_e32 v64, v136, v64, vcc
	v_lshlrev_b32_e32 v89, 2, v64
	v_xor_b32_e32 v64, 2, v136
	v_cmp_lt_i32_e32 vcc, v64, v68
	v_and_b32_e32 v113, 0xffff0000, v61
	v_mul_f32_e32 v61, 0xbfb8aa3b, v112
	v_cndmask_b32_e32 v64, v136, v64, vcc
	v_lshlrev_b32_e32 v102, 2, v64
	ds_read_b128 v[64:67], v134
	v_cmp_lt_i32_e32 vcc, v69, v68
	v_exp_f32_e32 v61, v61
	v_mul_f32_e32 v140, 0xbfb8aa3b, v113
	v_cndmask_b32_e32 v68, v136, v69, vcc
	v_lshlrev_b32_e32 v123, 2, v68
	ds_read_b128 v[68:71], v134 offset:4608
	s_waitcnt lgkmcnt(1)
	v_lshlrev_b32_e32 v108, 16, v66
	v_and_b32_e32 v109, 0xffff0000, v66
	v_lshlrev_b32_e32 v66, 16, v62
	v_lshlrev_b32_e32 v72, 16, v67
	v_and_b32_e32 v73, 0xffff0000, v67
	v_and_b32_e32 v67, 0xffff0000, v62
	v_mul_f32_e32 v62, 0xbfb8aa3b, v66
	v_exp_f32_e32 v110, v62
	v_mul_f32_e32 v62, 0xbfb8aa3b, v67
	v_exp_f32_e32 v111, v62
	v_exp_f32_e32 v140, v140
	v_add_f32_e32 v110, 1.0, v110
	v_rcp_f32_e32 v110, v110
	v_add_f32_e32 v111, 1.0, v111
	v_rcp_f32_e32 v111, v111
	v_add_f32_e32 v61, 1.0, v61
	v_and_b32_e32 v141, 0xffff0000, v65
	v_lshlrev_b32_e32 v74, 16, v63
	v_pk_mul_f32 v[66:67], v[110:111], v[66:67]
	v_rcp_f32_e32 v110, v61
	v_add_f32_e32 v61, 1.0, v140
	v_rcp_f32_e32 v111, v61
	v_lshlrev_b32_e32 v140, 16, v65
	v_and_b32_e32 v75, 0xffff0000, v63
	v_mul_f32_e32 v145, 0xbfb8aa3b, v75
	v_pk_mul_f32 v[110:111], v[110:111], v[112:113]
	v_lshlrev_b32_e32 v112, 16, v60
	v_and_b32_e32 v113, 0xffff0000, v60
	v_mul_f32_e32 v60, 0xbfb8aa3b, v112
	v_exp_f32_e32 v61, v60
	v_mul_f32_e32 v60, 0xbfb8aa3b, v113
	v_exp_f32_e32 v65, v60
	v_exp_f32_e32 v147, v145
	v_add_f32_e32 v61, 1.0, v61
	v_rcp_f32_e32 v144, v61
	v_add_f32_e32 v61, 1.0, v65
	v_mul_f32_e32 v65, 0xbfb8aa3b, v74
	v_exp_f32_e32 v65, v65
	v_rcp_f32_e32 v145, v61
	s_nop 0
	v_lshlrev_b32_e32 v156, 16, v57
	v_lshlrev_b32_e32 v60, 16, v64
	v_add_f32_e32 v61, 1.0, v65
	v_rcp_f32_e32 v146, v61
	v_add_f32_e32 v61, 1.0, v147
	v_rcp_f32_e32 v147, v61
	v_and_b32_e32 v61, 0xffff0000, v64
	v_mul_f32_e32 v155, 0xbfb8aa3b, v156
	s_waitcnt lgkmcnt(0)
	v_lshlrev_b32_e32 v164, 16, v68
	v_and_b32_e32 v165, 0xffff0000, v68
	v_pk_mul_f32 v[64:65], v[60:61], v[60:61]
	v_lshlrev_b32_e32 v150, 16, v70
	v_and_b32_e32 v151, 0xffff0000, v70
	v_lshlrev_b32_e32 v70, 16, v58
	v_lshlrev_b32_e32 v154, 16, v69
	v_exp_f32_e32 v159, v155
	v_and_b32_e32 v155, 0xffff0000, v69
	v_pk_mul_f32 v[68:69], v[164:165], v[164:165]
	v_pk_mul_f32 v[142:143], v[140:141], v[140:141]
	v_pk_mul_f32 v[112:113], v[144:145], v[112:113]
	v_lshlrev_b32_e32 v144, 16, v71
	v_and_b32_e32 v145, 0xffff0000, v71
	v_and_b32_e32 v71, 0xffff0000, v58
	v_mul_f32_e32 v58, 0xbfb8aa3b, v70
	v_pk_mul_f32 v[160:161], v[154:155], v[154:155]
	v_mov_b32_e32 v166, v68
	v_mov_b32_e32 v167, v64
	v_mov_b32_e32 v64, v69
	v_exp_f32_e32 v152, v58
	v_mul_f32_e32 v58, 0xbfb8aa3b, v71
	v_pk_add_f32 v[64:65], v[166:167], v[64:65]
	v_mov_b32_e32 v68, v160
	v_mov_b32_e32 v69, v142
	v_pk_mul_f32 v[62:63], v[108:109], v[108:109]
	v_pk_mul_f32 v[74:75], v[146:147], v[74:75]
	v_lshlrev_b32_e32 v146, 16, v59
	v_and_b32_e32 v147, 0xffff0000, v59
	v_exp_f32_e32 v153, v58
	v_pk_mul_f32 v[58:59], v[150:151], v[150:151]
	v_pk_add_f32 v[64:65], v[68:69], v[64:65]
	v_mov_b32_e32 v142, v161
	v_pk_add_f32 v[64:65], v[142:143], v[64:65]
	v_mov_b32_e32 v68, v58
	v_mov_b32_e32 v69, v62
	v_pk_mul_f32 v[106:107], v[72:73], v[72:73]
	v_pk_mul_f32 v[148:149], v[144:145], v[144:145]
	v_pk_add_f32 v[64:65], v[68:69], v[64:65]
	v_mov_b32_e32 v62, v59
	v_pk_add_f32 v[58:59], v[62:63], v[64:65]
	v_mov_b32_e32 v62, v148
	v_mov_b32_e32 v63, v106
	v_and_b32_e32 v157, 0xffff0000, v57
	v_add_f32_e32 v57, 1.0, v159
	v_pk_add_f32 v[58:59], v[62:63], v[58:59]
	v_mov_b32_e32 v106, v149
	v_rcp_f32_e32 v162, v57
	v_mul_f32_e32 v57, 0xbfb8aa3b, v157
	v_pk_add_f32 v[58:59], v[106:107], v[58:59]
	v_exp_f32_e32 v57, v57
	ds_bpermute_b32 v63, v89, v59
	ds_bpermute_b32 v62, v89, v58
	v_lshlrev_b32_e32 v64, 16, v56
	v_add_f32_e32 v57, 1.0, v57
	v_rcp_f32_e32 v163, v57
	v_and_b32_e32 v65, 0xffff0000, v56
	s_waitcnt lgkmcnt(0)
	v_pk_add_f32 v[56:57], v[58:59], v[62:63]
	ds_bpermute_b32 v59, v102, v57
	ds_bpermute_b32 v58, v102, v56
	v_mul_f32_e32 v62, 0xbfb8aa3b, v64
	v_mul_f32_e32 v63, 0xbfb8aa3b, v65
	v_exp_f32_e32 v62, v62
	v_exp_f32_e32 v63, v63
	s_waitcnt lgkmcnt(0)
	v_pk_add_f32 v[56:57], v[56:57], v[58:59]
	ds_bpermute_b32 v59, v123, v57
	ds_bpermute_b32 v58, v123, v56
	v_add_f32_e32 v62, 1.0, v62
	v_add_f32_e32 v63, 1.0, v63
	v_rcp_f32_e32 v62, v62
	v_rcp_f32_e32 v63, v63
	s_waitcnt lgkmcnt(0)
	v_pk_add_f32 v[56:57], v[56:57], v[58:59]
	v_lshl_add_u64 v[126:127], v[98:99], 0, v[126:127]
	v_pk_fma_f32 v[58:59], v[56:57], s[14:15], v[92:93] op_sel_hi:[1,0,0]
	v_pk_mul_f32 v[62:63], v[62:63], v[64:65]
	v_mul_f32_e32 v56, 0x4b800000, v59
	v_cmp_gt_f32_e32 vcc, s41, v59
	v_add_f32_e32 v152, 1.0, v152
	v_add_f32_e32 v153, 1.0, v153
	v_cndmask_b32_e32 v56, v59, v56, vcc
	v_rsq_f32_e32 v56, v56
	v_mul_f32_e32 v59, 0x4b800000, v58
	v_rcp_f32_e32 v152, v152
	v_rcp_f32_e32 v153, v153
	v_mul_f32_e32 v57, 0x45800000, v56
	v_cndmask_b32_e32 v56, v56, v57, vcc
	v_pk_mul_f32 v[60:61], v[56:57], v[60:61] op_sel_hi:[0,1]
	v_pk_mul_f32 v[60:61], v[4:5], v[60:61]
	v_pk_mul_f32 v[64:65], v[56:57], v[140:141] op_sel_hi:[0,1]
	v_pk_mul_f32 v[106:107], v[56:57], v[108:109] op_sel_hi:[0,1]
	v_pk_mul_f32 v[56:57], v[56:57], v[72:73] op_sel_hi:[0,1]
	v_cmp_gt_f32_e32 vcc, s41, v58
	v_pk_mul_f32 v[60:61], v[112:113], v[60:61]
	v_pk_mul_f32 v[56:57], v[2:3], v[56:57]
	v_cndmask_b32_e32 v58, v58, v59, vcc
	v_pk_mul_f32 v[72:73], v[74:75], v[56:57]
	v_cvt_pk_bf16_f32 v56, v60, v61
	v_rsq_f32_e32 v60, v58
	v_pk_mul_f32 v[64:65], v[6:7], v[64:65]
	v_pk_mul_f32 v[106:107], v[0:1], v[106:107]
	v_pk_mul_f32 v[64:65], v[110:111], v[64:65]
	v_pk_mul_f32 v[66:67], v[66:67], v[106:107]
	v_cvt_pk_bf16_f32 v57, v64, v65
	v_cvt_pk_bf16_f32 v58, v66, v67
	v_cvt_pk_bf16_f32 v59, v72, v73
	global_store_dwordx4 v[126:127], v[56:59], off offset:1024
	v_mul_f32_e32 v64, 0xbfb8aa3b, v147
	v_exp_f32_e32 v65, v64
	v_mul_f32_e32 v56, 0x45800000, v60
	v_cndmask_b32_e32 v56, v60, v56, vcc
	v_pk_mul_f32 v[58:59], v[56:57], v[164:165] op_sel_hi:[0,1]
	v_pk_mul_f32 v[58:59], v[4:5], v[58:59]
	v_pk_mul_f32 v[60:61], v[56:57], v[154:155] op_sel_hi:[0,1]
	v_pk_mul_f32 v[58:59], v[62:63], v[58:59]
	v_pk_mul_f32 v[62:63], v[56:57], v[150:151] op_sel_hi:[0,1]
	v_mul_f32_e32 v57, 0xbfb8aa3b, v146
	v_exp_f32_e32 v57, v57
	v_pk_mul_f32 v[68:69], v[152:153], v[70:71]
	v_pk_mul_f32 v[70:71], v[162:163], v[156:157]
	v_pk_mul_f32 v[60:61], v[6:7], v[60:61]
	v_add_f32_e32 v57, 1.0, v57
	v_rcp_f32_e32 v64, v57
	v_add_f32_e32 v57, 1.0, v65
	v_rcp_f32_e32 v65, v57
	v_pk_mul_f32 v[56:57], v[56:57], v[144:145] op_sel_hi:[0,1]
	v_pk_mul_f32 v[62:63], v[0:1], v[62:63]
	v_pk_mul_f32 v[56:57], v[2:3], v[56:57]
	v_pk_mul_f32 v[64:65], v[64:65], v[146:147]
	v_pk_mul_f32 v[60:61], v[70:71], v[60:61]
	v_pk_mul_f32 v[62:63], v[68:69], v[62:63]
	v_pk_mul_f32 v[64:65], v[64:65], v[56:57]
	v_cvt_pk_bf16_f32 v56, v58, v59
	v_cvt_pk_bf16_f32 v57, v60, v61
	v_cvt_pk_bf16_f32 v58, v62, v63
	v_cvt_pk_bf16_f32 v59, v64, v65
	v_lshl_add_u64 v[60:61], v[98:99], 0, v[124:125]
	global_store_dwordx4 v[60:61], v[56:59], off offset:1024
; #define SC_GATE(n) do { const int nn_ = (n) < 64 ? (n) : 63; _Pragma("unroll") for (int pp_ = 0; pp_ < 2; ++pp_) gt[pp_] = __builtin_nontemporal_load((const u32x4*)(PSg + (size_t)(b * T + 64 * nn_ + fr0 + 32 * pp_) * 1024 + h * 64 + 8 * fc8)); } while (0)
; DI void gdn_scan(int b, int h, const unsigned char* G, const float* glast, const bf16* PSg, const float* g_gdn, bf16* MIXA, LAS unsigned char* lds, int tid) {
;     ...
;         SC_GATE(n + 1);
;         SC_COMPUTE(n + 1, 1);
.LBB0_828:
	s_min_u32 s10, s50, 61
	s_add_i32 s10, s10, 2
	s_mul_i32 s23, s10, 0x50000
	s_add_u32 s52, s16, s23
	s_addc_u32 s53, s17, 0
	s_add_i32 s10, s10, s49
	s_nop 0
	v_add_u32_e32 v56, 64, v122
	v_add_u32_e32 v58, 0x60, v122
	v_lshl_add_u64 v[64:65], s[52:53], 0, v[76:77]
	v_mov_b32_e32 v89, v77
	s_lshl_b32 s10, s10, 3
	v_ashrrev_i32_e32 v57, 31, v56
	v_ashrrev_i32_e32 v59, 31, v58
	v_lshl_add_u64 v[64:65], v[64:65], 0, v[88:89]
	s_or_b32 s52, s10, s46
	v_lshlrev_b64 v[56:57], 11, v[56:57]
	v_lshlrev_b64 v[58:59], 11, v[58:59]
	v_lshl_add_u64 v[66:67], v[64:65], 0, s[12:13]
	v_add_co_u32_e32 v64, vcc, s40, v64
	s_ashr_i32 s53, s52, 31
	v_lshl_add_u64 v[56:57], v[96:97], 0, v[56:57]
	v_lshl_add_u64 v[58:59], v[96:97], 0, v[58:59]
	v_addc_co_u32_e32 v65, vcc, 0, v65, vcc
	s_lshl_b64 s[52:53], s[52:53], 2
	s_nop 0
	s_nop 0
	s_add_u32 s52, s33, s52
	s_addc_u32 s53, s96, s53
	s_and_b64 vcc, exec, s[0:1]
	s_cbranch_vccnz .LBB0_819
	v_add_u32_e32 v64, 0x9000, v130
	ds_read2_b64 v[140:143], v64 offset1:4
	v_add_u32_e32 v75, 0x9800, v130
	ds_read2_b64 v[148:151], v75 offset0:32 offset1:36
	s_nop 0
	v_lshlrev_b32_e32 v122, 16, v120
	v_and_b32_e32 v123, 0xffff0000, v120
	v_lshlrev_b32_e32 v124, 16, v121
	v_and_b32_e32 v125, 0xffff0000, v121
	v_cvt_pk_bf16_f32 v68, v24, v25
	v_cvt_pk_bf16_f32 v69, v26, v27
	v_cvt_pk_bf16_f32 v70, v28, v29
	v_cvt_pk_bf16_f32 v71, v30, v31
	ds_read2_b64 v[144:147], v64 offset0:8 offset1:12
	v_add_u32_e32 v89, 0xa000, v130
	s_waitcnt lgkmcnt(2)
	v_mfma_f32_16x16x32_bf16 v[120:123], v[140:143], v[68:71], v[122:125]
	ds_read2_b64 v[140:143], v89 offset0:64 offset1:68
	s_nop 0
	v_lshlrev_b32_e32 v72, 16, v118
	v_and_b32_e32 v73, 0xffff0000, v118
	ds_read2_b64 v[124:127], v75 offset0:40 offset1:44
	v_lshlrev_b32_e32 v74, 16, v119
	v_and_b32_e32 v75, 0xffff0000, v119
	v_cvt_pk_bf16_f32 v64, v32, v33
	v_cvt_pk_bf16_f32 v65, v34, v35
	s_waitcnt lgkmcnt(3)
	v_mfma_f32_16x16x32_bf16 v[72:75], v[148:151], v[68:71], v[72:75]
	v_cvt_pk_bf16_f32 v66, v36, v37
	v_cvt_pk_bf16_f32 v67, v38, v39
	s_nop 0
	v_pk_mul_f32 v[26:27], v[104:105], v[26:27] op_sel_hi:[0,1]
	v_pk_mul_f32 v[24:25], v[104:105], v[24:25] op_sel_hi:[0,1]
	s_waitcnt lgkmcnt(2)
	v_mfma_f32_16x16x32_bf16 v[120:123], v[144:147], v[64:67], v[120:123]
	v_lshlrev_b32_e32 v144, 16, v116
	v_and_b32_e32 v145, 0xffff0000, v116
	v_lshlrev_b32_e32 v146, 16, v117
	s_waitcnt lgkmcnt(0)
	v_mfma_f32_16x16x32_bf16 v[124:127], v[124:127], v[64:67], v[72:75]
	v_and_b32_e32 v147, 0xffff0000, v117
	v_pk_mul_f32 v[30:31], v[104:105], v[30:31] op_sel_hi:[0,1]
	v_pk_mul_f32 v[28:29], v[104:105], v[28:29] op_sel_hi:[0,1]
	ds_read2_b64 v[72:75], v89 offset0:72 offset1:76
	v_add_u32_e32 v89, 0xa800, v130
	v_mfma_f32_16x16x32_bf16 v[116:119], v[140:143], v[68:71], v[144:147]
	ds_read2_b64 v[140:143], v89 offset0:96 offset1:100
	ds_read2_b64 v[148:151], v89 offset0:104 offset1:108
	v_add_u32_e32 v89, 0xb000, v130
	v_lshlrev_b32_e32 v144, 16, v114
	v_and_b32_e32 v145, 0xffff0000, v114
	v_lshlrev_b32_e32 v146, 16, v115
	v_and_b32_e32 v147, 0xffff0000, v115
	s_waitcnt lgkmcnt(2)
	v_mfma_f32_16x16x32_bf16 v[116:119], v[72:75], v[64:67], v[116:119]
	v_add_u32_e32 v114, 0xd800, v130
	v_pk_mul_f32 v[34:35], v[104:105], v[34:35] op_sel_hi:[0,1]
	v_pk_mul_f32 v[32:33], v[104:105], v[32:33] op_sel_hi:[0,1]
	s_waitcnt lgkmcnt(1)
	v_mfma_f32_16x16x32_bf16 v[72:75], v[140:143], v[68:71], v[144:147]
	ds_read2_b64 v[140:143], v89 offset0:128 offset1:132
	s_nop 1
	v_cvt_pk_bf16_f32 v115, v118, v119
	v_pk_mul_f32 v[38:39], v[104:105], v[38:39] op_sel_hi:[0,1]
	s_waitcnt lgkmcnt(1)
	v_mfma_f32_16x16x32_bf16 v[144:147], v[148:151], v[64:67], v[72:75]
	ds_read2_b64 v[148:151], v114 offset1:4
	v_pk_mul_f32 v[36:37], v[104:105], v[36:37] op_sel_hi:[0,1]
	s_nop 0
	v_cvt_pk_bf16_f32 v72, v120, v121
	v_cvt_pk_bf16_f32 v73, v122, v123
	s_waitcnt lgkmcnt(1)
	v_mfma_f32_16x16x32_bf16 v[120:123], v[140:143], v[68:71], 0
	ds_read2_b64 v[140:143], v89 offset0:136 offset1:140
	v_cvt_pk_bf16_f32 v74, v124, v125
	v_cvt_pk_bf16_f32 v75, v126, v127
	ds_read2_b64 v[124:127], v114 offset0:8 offset1:12
	v_cvt_pk_bf16_f32 v114, v116, v117
	s_waitcnt lgkmcnt(2)
	v_mfma_f32_16x16x32_bf16 v[120:123], v[148:151], v[72:75], v[120:123]
	v_cvt_pk_bf16_f32 v116, v144, v145
	v_cvt_pk_bf16_f32 v117, v146, v147
	s_waitcnt lgkmcnt(1)
	v_mfma_f32_16x16x32_bf16 v[120:123], v[140:143], v[64:67], v[120:123]
	s_waitcnt lgkmcnt(0)
	v_mfma_f32_16x16x32_bf16 v[118:121], v[124:127], v[114:117], v[120:123]
	v_add_u32_e32 v126, 0xe000, v130
	s_nop 6
	v_cvt_pk_bf16_f32 v89, v118, s0
	ds_write_b16 v139, v89
	v_cvt_pk_bf16_f32 v89, v119, s0
	ds_write_b16 v139, v89 offset:144
	v_cvt_pk_bf16_f32 v89, v120, s0
	ds_write_b16 v139, v89 offset:288
	v_cvt_pk_bf16_f32 v89, v121, s0
	ds_write_b16 v139, v89 offset:432
	v_add_u32_e32 v89, 0xb800, v130
	ds_read2_b64 v[118:121], v89 offset0:160 offset1:164
	ds_read2_b64 v[122:125], v126 offset0:32 offset1:36
	s_waitcnt lgkmcnt(1)
	v_mfma_f32_16x16x32_bf16 v[118:121], v[118:121], v[68:71], 0
	s_waitcnt lgkmcnt(0)
	v_mfma_f32_16x16x32_bf16 v[118:121], v[122:125], v[72:75], v[118:121]
	ds_read2_b64 v[122:125], v89 offset0:168 offset1:172
	s_waitcnt lgkmcnt(0)
	v_mfma_f32_16x16x32_bf16 v[118:121], v[122:125], v[64:67], v[118:121]
	ds_read2_b64 v[122:125], v126 offset0:40 offset1:44
	v_add_u32_e32 v126, 0xe800, v130
	s_waitcnt lgkmcnt(0)
	v_mfma_f32_16x16x32_bf16 v[118:121], v[122:125], v[114:117], v[118:121]
	s_nop 7
	v_cvt_pk_bf16_f32 v89, v118, s0
	ds_write_b16 v139, v89 offset:2304
	v_cvt_pk_bf16_f32 v89, v119, s0
	ds_write_b16 v139, v89 offset:2448
	v_cvt_pk_bf16_f32 v89, v120, s0
	ds_write_b16 v139, v89 offset:2592
	v_cvt_pk_bf16_f32 v89, v121, s0
	ds_write_b16 v139, v89 offset:2736
	v_add_u32_e32 v89, 0xc000, v130
	ds_read2_b64 v[118:121], v89 offset0:192 offset1:196
	ds_read2_b64 v[122:125], v126 offset0:64 offset1:68
	s_waitcnt lgkmcnt(1)
; DI void gdn_scan(int b, int h, const unsigned char* G, const float* glast, const bf16* PSg, const float* g_gdn, bf16* MIXA, LAS unsigned char* lds, int tid) {
;     ...
;     SC_FLUSH(63, 1);
	v_mfma_f32_16x16x32_bf16 v[118:121], v[118:121], v[68:71], 0
	s_waitcnt lgkmcnt(0)
	v_mfma_f32_16x16x32_bf16 v[118:121], v[122:125], v[72:75], v[118:121]
	ds_read2_b64 v[122:125], v89 offset0:200 offset1:204
	s_waitcnt lgkmcnt(0)
	v_mfma_f32_16x16x32_bf16 v[118:121], v[122:125], v[64:67], v[118:121]
	ds_read2_b64 v[122:125], v126 offset0:72 offset1:76
	s_waitcnt lgkmcnt(0)
	v_mfma_f32_16x16x32_bf16 v[118:121], v[122:125], v[114:117], v[118:121]
	v_add_u32_e32 v122, 0xf000, v130
	s_nop 6
	v_cvt_pk_bf16_f32 v89, v118, s0
	ds_write_b16 v139, v89 offset:4608
	v_cvt_pk_bf16_f32 v89, v119, s0
	ds_write_b16 v139, v89 offset:4752
	v_cvt_pk_bf16_f32 v89, v120, s0
	ds_write_b16 v139, v89 offset:4896
	v_cvt_pk_bf16_f32 v89, v121, s0
	ds_write_b16 v139, v89 offset:5040
	v_add_u32_e32 v89, 0xc800, v130
	ds_read2_b64 v[118:121], v89 offset0:224 offset1:228
	s_waitcnt lgkmcnt(0)
	v_mfma_f32_16x16x32_bf16 v[68:71], v[118:121], v[68:71], 0
	ds_read2_b64 v[118:121], v122 offset0:96 offset1:100
	s_waitcnt lgkmcnt(0)
	v_mfma_f32_16x16x32_bf16 v[68:71], v[118:121], v[72:75], v[68:71]
	ds_read2_b64 v[118:121], v89 offset0:232 offset1:236
	s_waitcnt lgkmcnt(0)
	v_mfma_f32_16x16x32_bf16 v[64:67], v[118:121], v[64:67], v[68:71]
	s_nop 4
	ds_read2_b64 v[68:71], v122 offset0:104 offset1:108
	s_waitcnt lgkmcnt(0)
	v_mfma_f32_16x16x32_bf16 v[64:67], v[68:71], v[114:117], v[64:67]
	v_add_u32_e32 v68, 0xf800, v130
	s_nop 6
	v_cvt_pk_bf16_f32 v64, v64, s0
	ds_write_b16 v139, v64 offset:6912
	v_cvt_pk_bf16_f32 v64, v65, s0
	ds_write_b16 v139, v64 offset:7056
	v_cvt_pk_bf16_f32 v64, v66, s0
	ds_write_b16 v139, v64 offset:7200
	v_cvt_pk_bf16_f32 v64, v67, s0
	ds_write_b16 v139, v64 offset:7344
	ds_read2_b64 v[64:67], v68 offset0:128 offset1:132
	s_waitcnt lgkmcnt(0)
	v_mfma_f32_16x16x32_bf16 v[24:27], v[64:67], v[72:75], v[24:27]
	ds_read2_b64 v[64:67], v68 offset0:136 offset1:140
	v_add_u32_e32 v68, 0x800, v135
	s_waitcnt lgkmcnt(0)
	v_mfma_f32_16x16x32_bf16 v[24:27], v[64:67], v[114:117], v[24:27]
	ds_read2_b64 v[64:67], v68 offset0:32 offset1:36
	s_waitcnt lgkmcnt(0)
	v_mfma_f32_16x16x32_bf16 v[28:31], v[64:67], v[72:75], v[28:31]
	ds_read2_b64 v[64:67], v68 offset0:40 offset1:44
	v_add_u32_e32 v68, 0x1000, v135
	s_waitcnt lgkmcnt(0)
	v_mfma_f32_16x16x32_bf16 v[28:31], v[64:67], v[114:117], v[28:31]
	ds_read2_b64 v[64:67], v68 offset0:64 offset1:68
	s_waitcnt lgkmcnt(0)
	v_mfma_f32_16x16x32_bf16 v[32:35], v[64:67], v[72:75], v[32:35]
	ds_read2_b64 v[64:67], v68 offset0:72 offset1:76
	v_add_u32_e32 v68, 0x1800, v135
	s_waitcnt lgkmcnt(0)
	v_mfma_f32_16x16x32_bf16 v[32:35], v[64:67], v[114:117], v[32:35]
	ds_read2_b64 v[64:67], v68 offset0:96 offset1:100
	s_waitcnt lgkmcnt(0)
	v_mfma_f32_16x16x32_bf16 v[36:39], v[64:67], v[72:75], v[36:39]
	ds_read2_b64 v[64:67], v68 offset0:104 offset1:108
	s_waitcnt lgkmcnt(0)
	v_mfma_f32_16x16x32_bf16 v[36:39], v[64:67], v[114:117], v[36:39]
	s_branch .LBB0_819
.LBB0_830:
	s_and_b64 vcc, exec, s[2:3]
	s_cbranch_vccnz .LBB0_817
	s_waitcnt vmcnt(0)
	v_mov_b64_e32 v[60:61], v[168:169]
	v_mov_b64_e32 v[62:63], v[170:171]
	v_mov_b64_e32 v[56:57], v[172:173]
	v_mov_b64_e32 v[58:59], v[174:175]
	s_waitcnt vmcnt(10)
	v_and_b32_e32 v9, 64, v136
	v_xor_b32_e32 v8, 1, v136
	s_waitcnt vmcnt(9)
	v_add_u32_e32 v12, 64, v9
	v_cmp_lt_i32_e32 vcc, v8, v12
	v_add_u32_e32 v14, v105, v128
	s_waitcnt vmcnt(6)
	v_lshlrev_b32_e32 v28, 16, v61
	v_cndmask_b32_e32 v8, v136, v8, vcc
	v_lshlrev_b32_e32 v64, 2, v8
	v_xor_b32_e32 v8, 2, v136
	v_cmp_lt_i32_e32 vcc, v8, v12
	v_and_b32_e32 v29, 0xffff0000, v61
	v_mul_f32_e32 v30, 0xbfb8aa3b, v28
	v_cndmask_b32_e32 v8, v136, v8, vcc
	v_lshlrev_b32_e32 v65, 2, v8
	ds_read_b128 v[8:11], v14
	v_mul_f32_e32 v31, 0xbfb8aa3b, v29
	v_exp_f32_e32 v30, v30
	v_exp_f32_e32 v31, v31
	v_lshlrev_b32_e32 v18, 16, v63
	s_waitcnt lgkmcnt(0)
	v_lshlrev_b32_e32 v22, 16, v10
	v_and_b32_e32 v23, 0xffff0000, v10
	v_lshlrev_b32_e32 v10, 16, v62
	v_lshlrev_b32_e32 v16, 16, v11
	v_and_b32_e32 v17, 0xffff0000, v11
	v_and_b32_e32 v11, 0xffff0000, v62
	v_mul_f32_e32 v24, 0xbfb8aa3b, v10
	v_exp_f32_e32 v26, v24
	v_mul_f32_e32 v24, 0xbfb8aa3b, v11
	v_exp_f32_e32 v27, v24
	v_and_b32_e32 v19, 0xffff0000, v63
	v_add_f32_e32 v26, 1.0, v26
	v_rcp_f32_e32 v26, v26
	v_add_f32_e32 v27, 1.0, v27
	v_rcp_f32_e32 v27, v27
	v_mul_f32_e32 v37, 0xbfb8aa3b, v19
	v_exp_f32_e32 v39, v37
	v_xor_b32_e32 v13, 4, v136
	v_pk_mul_f32 v[10:11], v[26:27], v[10:11]
	v_add_f32_e32 v26, 1.0, v30
	v_add_f32_e32 v27, 1.0, v31
	v_rcp_f32_e32 v26, v26
	v_rcp_f32_e32 v27, v27
	v_lshlrev_b32_e32 v30, 16, v9
	v_and_b32_e32 v31, 0xffff0000, v9
	v_cmp_lt_i32_e32 vcc, v13, v12
	v_pk_mul_f32 v[26:27], v[26:27], v[28:29]
	v_lshlrev_b32_e32 v28, 16, v60
	v_and_b32_e32 v29, 0xffff0000, v60
	v_mul_f32_e32 v9, 0xbfb8aa3b, v28
	v_exp_f32_e32 v9, v9
	v_mul_f32_e32 v34, 0xbfb8aa3b, v29
	v_exp_f32_e32 v35, v34
	v_cndmask_b32_e32 v12, v136, v13, vcc
	v_add_f32_e32 v9, 1.0, v9
	v_rcp_f32_e32 v36, v9
	v_add_f32_e32 v9, 1.0, v35
	v_mul_f32_e32 v35, 0xbfb8aa3b, v18
	v_exp_f32_e32 v35, v35
	v_rcp_f32_e32 v37, v9
	v_lshlrev_b32_e32 v66, 2, v12
	ds_read_b128 v[12:15], v14 offset:4608
	v_add_f32_e32 v9, 1.0, v35
	v_rcp_f32_e32 v38, v9
	v_add_f32_e32 v9, 1.0, v39
	v_rcp_f32_e32 v39, v9
	s_waitcnt vmcnt(5)
	v_lshlrev_b32_e32 v52, 16, v57
	v_mul_f32_e32 v51, 0xbfb8aa3b, v52
	s_waitcnt lgkmcnt(0)
; DI void gdn_scan(int b, int h, const unsigned char* G, const float* glast, const bf16* PSg, const float* g_gdn, bf16* MIXA, LAS unsigned char* lds, int tid) {
;     ...
;     SC_FLUSH(63, 1);
;     __syncthreads();
	v_lshlrev_b32_e32 v44, 16, v14
	v_pk_mul_f32 v[18:19], v[38:39], v[18:19]
	v_lshlrev_b32_e32 v38, 16, v15
	v_and_b32_e32 v39, 0xffff0000, v15
	v_and_b32_e32 v45, 0xffff0000, v14
	v_lshlrev_b32_e32 v14, 16, v58
	v_and_b32_e32 v15, 0xffff0000, v58
	v_exp_f32_e32 v58, v51
	v_lshlrev_b32_e32 v50, 16, v13
	v_and_b32_e32 v51, 0xffff0000, v13
	v_and_b32_e32 v53, 0xffff0000, v57
	v_add_f32_e32 v13, 1.0, v58
	v_lshlrev_b32_e32 v34, 16, v8
	v_and_b32_e32 v35, 0xffff0000, v8
	v_rcp_f32_e32 v58, v13
	v_mul_f32_e32 v13, 0xbfb8aa3b, v53
	v_lshlrev_b32_e32 v60, 16, v12
	v_and_b32_e32 v61, 0xffff0000, v12
	v_pk_mul_f32 v[8:9], v[34:35], v[34:35]
	v_exp_f32_e32 v57, v13
	v_pk_mul_f32 v[12:13], v[60:61], v[60:61]
	v_pk_mul_f32 v[32:33], v[30:31], v[30:31]
	v_mul_f32_e32 v46, 0xbfb8aa3b, v14
	v_pk_mul_f32 v[54:55], v[50:51], v[50:51]
	v_mov_b32_e32 v62, v12
	v_mov_b32_e32 v63, v8
	v_mov_b32_e32 v8, v13
	v_exp_f32_e32 v48, v46
	v_mul_f32_e32 v46, 0xbfb8aa3b, v15
	v_pk_add_f32 v[8:9], v[62:63], v[8:9]
	v_mov_b32_e32 v12, v54
	v_mov_b32_e32 v13, v32
	v_pk_mul_f32 v[24:25], v[22:23], v[22:23]
	v_exp_f32_e32 v49, v46
	v_pk_mul_f32 v[46:47], v[44:45], v[44:45]
	v_pk_add_f32 v[8:9], v[12:13], v[8:9]
	v_mov_b32_e32 v32, v55
	v_pk_add_f32 v[8:9], v[32:33], v[8:9]
	v_mov_b32_e32 v12, v46
	v_mov_b32_e32 v13, v24
	v_pk_mul_f32 v[20:21], v[16:17], v[16:17]
	v_pk_mul_f32 v[42:43], v[38:39], v[38:39]
	v_pk_add_f32 v[8:9], v[12:13], v[8:9]
	v_mov_b32_e32 v24, v47
	v_pk_add_f32 v[8:9], v[24:25], v[8:9]
	v_mov_b32_e32 v12, v42
	v_mov_b32_e32 v13, v20
	v_pk_add_f32 v[8:9], v[12:13], v[8:9]
	v_mov_b32_e32 v20, v43
	v_pk_add_f32 v[8:9], v[20:21], v[8:9]
	ds_bpermute_b32 v13, v64, v9
	ds_bpermute_b32 v12, v64, v8
	v_add_f32_e32 v20, 1.0, v57
	v_lshlrev_b32_e32 v40, 16, v59
	v_and_b32_e32 v41, 0xffff0000, v59
	v_rcp_f32_e32 v59, v20
	s_waitcnt lgkmcnt(0)
	v_pk_add_f32 v[8:9], v[8:9], v[12:13]
	ds_bpermute_b32 v13, v65, v9
	ds_bpermute_b32 v12, v65, v8
	v_lshlrev_b32_e32 v20, 16, v56
	v_and_b32_e32 v21, 0xffff0000, v56
	v_mul_f32_e32 v24, 0xbfb8aa3b, v20
	v_mul_f32_e32 v25, 0xbfb8aa3b, v21
	s_waitcnt lgkmcnt(0)
	v_pk_add_f32 v[8:9], v[8:9], v[12:13]
	ds_bpermute_b32 v13, v66, v9
	ds_bpermute_b32 v12, v66, v8
	v_exp_f32_e32 v24, v24
	v_exp_f32_e32 v25, v25
	s_or_b32 s0, s47, 0xfc0
	v_pk_mul_f32 v[28:29], v[36:37], v[28:29]
	s_waitcnt lgkmcnt(0)
	v_pk_add_f32 v[8:9], v[8:9], v[12:13]
	v_add_f32_e32 v24, 1.0, v24
	v_pk_fma_f32 v[12:13], v[8:9], s[14:15], v[92:93] op_sel_hi:[1,0,0]
	v_add_f32_e32 v25, 1.0, v25
	v_mul_f32_e32 v8, 0x4b800000, v13
	v_cmp_gt_f32_e32 vcc, s41, v13
	v_rcp_f32_e32 v24, v24
	v_rcp_f32_e32 v25, v25
	v_cndmask_b32_e32 v8, v13, v8, vcc
	v_rsq_f32_e32 v8, v8
	v_or_b32_e32 v36, s0, v103
	v_pk_mul_f32 v[20:21], v[24:25], v[20:21]
	v_mul_f32_e32 v13, 0x4b800000, v12
	v_mul_f32_e32 v9, 0x45800000, v8
	v_cndmask_b32_e32 v8, v8, v9, vcc
	v_pk_mul_f32 v[24:25], v[8:9], v[34:35] op_sel_hi:[0,1]
	v_cmp_gt_f32_e32 vcc, s41, v12
	v_ashrrev_i32_e32 v37, 31, v36
	v_readlane_b32 s2, v253, 45
	v_pk_mul_f32 v[24:25], v[4:5], v[24:25]
	v_cndmask_b32_e32 v12, v12, v13, vcc
	v_lshlrev_b64 v[36:37], 11, v[36:37]
	v_readlane_b32 s3, v253, 46
	v_pk_mul_f32 v[24:25], v[28:29], v[24:25]
	v_pk_mul_f32 v[28:29], v[8:9], v[30:31] op_sel_hi:[0,1]
	v_pk_mul_f32 v[22:23], v[8:9], v[22:23] op_sel_hi:[0,1]
	v_pk_mul_f32 v[8:9], v[8:9], v[16:17] op_sel_hi:[0,1]
	v_rsq_f32_e32 v12, v12
	v_lshl_add_u64 v[36:37], s[2:3], 0, v[36:37]
	s_lshl_b32 s10, s45, 1
	v_pk_mul_f32 v[28:29], v[6:7], v[28:29]
	v_pk_mul_f32 v[22:23], v[0:1], v[22:23]
	v_pk_mul_f32 v[8:9], v[2:3], v[8:9]
	v_lshl_add_u64 v[36:37], v[36:37], 0, s[10:11]
	v_mov_b32_e32 v159, v77
	v_pk_mul_f32 v[26:27], v[26:27], v[28:29]
	v_pk_mul_f32 v[10:11], v[10:11], v[22:23]
	v_pk_mul_f32 v[16:17], v[18:19], v[8:9]
	v_lshl_add_u64 v[36:37], v[36:37], 0, v[158:159]
	v_cvt_pk_bf16_f32 v8, v24, v25
	v_cvt_pk_bf16_f32 v9, v26, v27
	v_cvt_pk_bf16_f32 v10, v10, v11
	v_cvt_pk_bf16_f32 v11, v16, v17
	global_store_dwordx4 v[36:37], v[8:11], off offset:1024
	v_add_f32_e32 v48, 1.0, v48
	v_add_f32_e32 v49, 1.0, v49
	v_mul_f32_e32 v8, 0x45800000, v12
	v_cndmask_b32_e32 v8, v12, v8, vcc
	v_pk_mul_f32 v[10:11], v[8:9], v[60:61] op_sel_hi:[0,1]
	v_pk_mul_f32 v[4:5], v[4:5], v[10:11]
	v_pk_mul_f32 v[10:11], v[8:9], v[50:51] op_sel_hi:[0,1]
	v_pk_mul_f32 v[6:7], v[6:7], v[10:11]
	v_pk_mul_f32 v[10:11], v[8:9], v[44:45] op_sel_hi:[0,1]
	v_mul_f32_e32 v9, 0xbfb8aa3b, v40
	v_exp_f32_e32 v9, v9
	v_mul_f32_e32 v12, 0xbfb8aa3b, v41
	v_exp_f32_e32 v12, v12
	v_rcp_f32_e32 v48, v48
	v_rcp_f32_e32 v49, v49
	v_add_f32_e32 v9, 1.0, v9
	v_pk_mul_f32 v[0:1], v[0:1], v[10:11]
	v_rcp_f32_e32 v10, v9
	v_add_f32_e32 v9, 1.0, v12
	v_rcp_f32_e32 v11, v9
	v_pk_mul_f32 v[14:15], v[48:49], v[14:15]
	v_pk_mul_f32 v[4:5], v[20:21], v[4:5]
	v_pk_mul_f32 v[12:13], v[14:15], v[0:1]
	v_pk_mul_f32 v[0:1], v[8:9], v[38:39] op_sel_hi:[0,1]
	v_pk_mul_f32 v[0:1], v[2:3], v[0:1]
	v_pk_mul_f32 v[2:3], v[10:11], v[40:41]
	v_pk_mul_f32 v[32:33], v[58:59], v[52:53]
	v_pk_mul_f32 v[8:9], v[2:3], v[0:1]
	v_cvt_pk_bf16_f32 v0, v4, v5
	v_or_b32_e32 v4, s0, v129
	v_ashrrev_i32_e32 v5, 31, v4
	v_lshlrev_b64 v[4:5], 11, v[4:5]
	v_lshl_add_u64 v[4:5], s[2:3], 0, v[4:5]
	v_pk_mul_f32 v[6:7], v[32:33], v[6:7]
	v_lshl_add_u64 v[4:5], v[4:5], 0, s[10:11]
	v_cvt_pk_bf16_f32 v1, v6, v7
	v_cvt_pk_bf16_f32 v2, v12, v13
	v_cvt_pk_bf16_f32 v3, v8, v9
	v_lshl_add_u64 v[4:5], v[4:5], 0, v[158:159]
	global_store_dwordx4 v[4:5], v[0:3], off offset:1024
	s_branch .LBB0_817
